# attention: 8 query-block workgroups of one batch-head mapped to one XCD for L2 sharing of K/V
# speedup vs baseline: 1.0069x; 1.0069x over previous
; DI void phase_attention(KParams P, LAS unsigned char* lds) {
;     ...
;   { const float s1 = wave_sum(P->lq1[lane] * P->lk1[lane]), s2 = wave_sum(P->lq2[lane] * P->lk2[lane]); lam = __expf(s1) - __expf(s2) + 0.2f; }
;   const int G = gridDim.x;
;   const int vb = (int)blockIdx.x;
;   const float LOG2E = 1.4426950408889634f;
;     ...
;   for (int it = vb; it < 256; it += G) {
.LBB0_90:
	s_andn2_b64 vcc, exec, s[4:5]
	s_cbranch_vccnz .LBB0_149
	v_readlane_b32 s4, v250, 25
	s_cmp_eq_u32 s4, 5
	v_readlane_b32 s5, v250, 26
	s_cbranch_scc0 .LBB0_149
	v_mov_b32_e32 v0, v163
	v_mov_b32_e32 v2, v163
	s_waitcnt lgkmcnt(0)
	s_load_dwordx8 s[40:47], s[0:1], 0x30
	v_and_b32_e32 v3, 63, v0
	v_lshlrev_b32_e32 v3, 2, v3
	s_waitcnt lgkmcnt(0)
	global_load_dword v4, v3, s[40:41]
	global_load_dword v5, v3, s[42:43]
	global_load_dword v6, v3, s[44:45]
	s_nop 0
	global_load_dword v3, v3, s[46:47]
	v_cmp_lt_i32_e32 vcc, v193, v192
	v_readlane_b32 s4, v251, 7
	v_readlane_b32 s5, v251, 8
	v_cndmask_b32_e32 v7, v191, v193, vcc
	v_lshlrev_b32_e32 v151, 2, v7
	v_cmp_lt_i32_e32 vcc, v194, v192
	s_waitcnt vmcnt(0)
	v_mul_f32_e32 v7, v4, v5
	ds_bpermute_b32 v7, v151, v7
	v_mul_f32_e32 v8, v6, v3
	ds_bpermute_b32 v8, v151, v8
	v_cndmask_b32_e32 v9, v191, v194, vcc
	v_lshlrev_b32_e32 v9, 2, v9
	s_waitcnt lgkmcnt(1)
	v_fmac_f32_e32 v7, v4, v5
	v_cmp_lt_i32_e32 vcc, v195, v192
	s_waitcnt lgkmcnt(0)
	v_fmac_f32_e32 v8, v6, v3
	ds_bpermute_b32 v3, v9, v7
	ds_bpermute_b32 v4, v9, v8
	v_cndmask_b32_e32 v5, v191, v195, vcc
	v_lshlrev_b32_e32 v5, 2, v5
	v_cmp_lt_i32_e32 vcc, v196, v192
	s_waitcnt lgkmcnt(1)
	v_add_f32_e32 v3, v7, v3
	s_waitcnt lgkmcnt(0)
	v_add_f32_e32 v4, v8, v4
	ds_bpermute_b32 v6, v5, v3
	ds_bpermute_b32 v5, v5, v4
	v_cndmask_b32_e32 v7, v191, v196, vcc
	v_lshlrev_b32_e32 v7, 2, v7
	v_cmp_lt_i32_e32 vcc, v197, v192
	s_waitcnt lgkmcnt(1)
	v_add_f32_e32 v3, v3, v6
	s_waitcnt lgkmcnt(0)
	v_add_f32_e32 v4, v4, v5
	ds_bpermute_b32 v5, v7, v3
	ds_bpermute_b32 v6, v7, v4
	v_cndmask_b32_e32 v7, v191, v197, vcc
	v_lshlrev_b32_e32 v7, 2, v7
	v_cmp_lt_i32_e32 vcc, v198, v192
	s_waitcnt lgkmcnt(1)
	v_add_f32_e32 v3, v3, v5
	s_waitcnt lgkmcnt(0)
	v_add_f32_e32 v4, v4, v6
	ds_bpermute_b32 v5, v7, v3
	ds_bpermute_b32 v6, v7, v4
	v_cndmask_b32_e32 v7, v191, v198, vcc
	v_lshlrev_b32_e32 v7, 2, v7
	s_andn2_b64 vcc, exec, s[4:5]
	s_waitcnt lgkmcnt(1)
	v_add_f32_e32 v3, v3, v5
	s_waitcnt lgkmcnt(0)
	v_add_f32_e32 v4, v4, v6
	ds_bpermute_b32 v5, v7, v3
	ds_bpermute_b32 v6, v7, v4
	s_cbranch_vccnz .LBB0_149
	s_waitcnt lgkmcnt(1)
	v_add_f32_e32 v3, v3, v5
	s_waitcnt lgkmcnt(0)
	v_add_f32_e32 v4, v4, v6
	v_mul_f32_e32 v3, 0x3fb8aa3b, v3
	v_mul_f32_e32 v4, 0x3fb8aa3b, v4
	v_exp_f32_e32 v3, v3
	v_exp_f32_e32 v4, v4
	s_load_dword s3, s[68:69], 0x0
	v_ashrrev_i32_e32 v2, 1, v2
	s_movk_i32 s4, 0xffe0
	v_sub_f32_e32 v3, v3, v4
	v_add_f32_e32 v148, 0x3e4ccccd, v3
	v_lshrrev_b32_e32 v3, 3, v0
	v_and_b32_e32 v150, 4, v3
	v_bfi_b32 v165, s4, v2, v0
	v_mov_b32_e32 v149, v148
	v_readlane_b32 s17, v251, 0
	s_waitcnt lgkmcnt(0)
	s_cmp_lg_u32 s3, 0x100
	s_cbranch_scc1 .Lxr_a
	s_and_b32 s4, s17, 7
	s_lshl_b32 s4, s4, 5
	s_lshr_b32 s5, s17, 3
	s_or_b32 s17, s4, s5
.Lxr_a:
	s_branch .LBB0_95
.LBB0_94:
	s_add_i32 s17, s17, s3
	s_cmpk_lt_i32 s17, 0x100
	s_cbranch_scc0 .LBB0_119

; template <int DK>
; DI void attn_pass(const AttnSrc& s, const int q0, const float sc, LAS unsigned char* lds, f32x16 (&O)[4]) {
;     ...
;   const bf16_t* kp[KP]; int kstr[KP]; const bf16_t* vp[2];
; #pragma unroll
;   for (int i = 0; i < KP; ++i) {
;     const int o = (wid + 8 * i) * 1024 + lane * 16, row = o / ROWB, pc = (o % ROWB) >> 4;
;     const int lc = (DK == 64) ? (pc ^ (row & 7)) : ((pc & ~7) | ((pc & 7) ^ ((row >> 1) & 7)));
;     const int e = lc * 8;
;     if (e < s.nk0) { kp[i] = s.k0 + (size_t)row * s.ldk0 + e; kstr[i] = 64 * s.ldk0; } else { kp[i] = s.k1 + (size_t)row * s.ldk1 + (e - s.nk0); kstr[i] = 64 * s.ldk1; }
;   }
; #pragma unroll
;   for (int i = 0; i < 2; ++i) {
;     const int o = (wid + 8 * i) * 1024 + lane * 16, row = o >> 8, pc = (o >> 4) & 15;
;     const int lc = (((pc >> 2) ^ (row & 3)) << 2) | (pc & 3);
;     vp[i] = s.v + (size_t)row * s.ldv + lc * 8;
;   }
;   const int vstr = 64 * s.ldv;
;   const unsigned lds0 = (unsigned)reinterpret_cast<__UINTPTR_TYPE__>(lds);
;   auto issue = [&](int t, int buf) {
; #pragma unroll
;     for (int i = 0; i < KP; ++i) glds16(kp[i] + (size_t)t * kstr[i], (unsigned)__builtin_amdgcn_readfirstlane(lds0 + buf * STG + (wid + 8 * i) * 1024));
; #pragma unroll
;     for (int i = 0; i < 2; ++i) glds16(vp[i] + (size_t)t * vstr, (unsigned)__builtin_amdgcn_readfirstlane(lds0 + buf * STG + KSZ + (wid + 8 * i) * 1024));
;   };
; #pragma unroll
;   for (int i = 0; i < DPF; ++i) issue(i, i);
;   bf16x8 qf[NS];
; #pragma unroll
;   for (int i = 0; i < NS; ++i) qf[i] = *(const bf16x8*)(s.q + (size_t)(qw0 + r) * s.ldq + 16 * i + 8 * h);
.LBB0_99:
	s_xor_b64 s[10:11], s[12:13], -1
	s_lshl_b64 s[14:15], s[14:15], 1
	v_mov_b32_e32 v24, v163
	s_add_u32 s14, s22, s14
	s_addc_u32 s15, s23, s15
	v_readfirstlane_b32 s18, v24
	s_ashr_i32 s18, s18, 6
	s_lshl_b32 s45, s18, 5
	v_and_b32_e32 v0, 63, v24
	s_lshl_b32 s18, s18, 10
	v_lshl_or_b32 v8, v0, 4, s18
	v_ashrrev_i32_e32 v0, 31, v8
	v_lshrrev_b32_e32 v0, 25, v0
	v_add_u32_e32 v0, v8, v0
	v_ashrrev_i32_e32 v3, 7, v0
	v_and_b32_e32 v0, 0xffffff80, v0
	v_sub_u32_e32 v0, v8, v0
	v_ashrrev_i32_e32 v0, 4, v0
	v_bitop3_b32 v9, v0, v3, 7 bitop3:0x78
	v_lshlrev_b32_e32 v2, 3, v9
	v_mov_b64_e32 v[4:5], s[14:15]
	v_mad_i64_i32 v[6:7], s[14:15], v3, s59, v[4:5]
	v_ashrrev_i32_e32 v3, 31, v2
	v_ashrrev_i32_e32 v0, 8, v8
	v_lshl_add_u64 v[2:3], v[2:3], 1, v[6:7]
	v_lshlrev_b32_e32 v6, 2, v0
	v_and_b32_e32 v10, 3, v24
	v_xor_b32_e32 v6, v6, v24
	v_and_or_b32 v11, v6, 12, v10
	v_mul_hi_i32_i24_e32 v7, 0x1800, v0
	v_mul_i32_i24_e32 v6, 0x1800, v0
	v_lshl_add_u64 v[6:7], s[4:5], 0, v[6:7]
	v_lshlrev_b32_e32 v0, 4, v11
	v_lshl_add_u64 v[18:19], v[6:7], 0, v[0:1]
	v_add_u32_e32 v0, 0x2000, v8
	v_ashrrev_i32_e32 v0, 8, v0
	v_lshlrev_b32_e32 v6, 2, v0
	v_xor_b32_e32 v6, v6, v24
	v_and_or_b32 v8, v6, 12, v10
	v_mul_hi_i32_i24_e32 v7, 0x1800, v0
	v_mul_i32_i24_e32 v6, 0x1800, v0
	v_lshl_add_u64 v[6:7], s[4:5], 0, v[6:7]
	v_lshlrev_b32_e32 v0, 4, v8
	v_cmp_gt_i32_e32 vcc, 8, v9
	v_lshl_add_u64 v[20:21], v[6:7], 0, v[0:1]
	s_waitcnt vmcnt(0)
	s_mov_b64 s[14:15], 0x800
	v_cndmask_b32_e64 v7, -1, 0, vcc
	v_cndmask_b32_e64 v6, v200, 0, vcc
	v_lshl_add_u64 v[22:23], v[2:3], 0, v[6:7]
	v_lshl_add_u64 v[2:3], v[22:23], 0, s[14:15]
	s_add_i32 s46, s18, 0
	s_mov_b32 s14, m0
	s_mov_b32 m0, s46
	s_nop 0
	global_load_lds_dwordx4 v[2:3], off
	s_mov_b32 m0, s14
	s_add_i32 s47, s46, 0x2000
	s_mov_b32 s14, m0
	s_mov_b32 m0, s47
	s_nop 0
	global_load_lds_dwordx4 v[18:19], off
	s_mov_b32 m0, s14
	s_add_i32 s52, s46, 0x4000
	s_mov_b32 s14, m0
	s_mov_b32 m0, s52
	s_nop 0
	global_load_lds_dwordx4 v[20:21], off
	s_mov_b32 m0, s14
	s_mov_b64 s[14:15], 0x60800
	v_lshl_add_u64 v[2:3], v[22:23], 0, s[14:15]
	s_add_i32 s14, s46, 0x6000
	s_mov_b32 s15, m0
	s_mov_b32 m0, s14
	s_nop 0
	global_load_lds_dwordx4 v[2:3], off
	s_mov_b32 m0, s15
	v_lshl_add_u64 v[2:3], v[18:19], 0, s[26:27]
	s_add_i32 s14, s46, 0x8000
	s_mov_b32 s15, m0
	s_mov_b32 m0, s14
	s_nop 0
	global_load_lds_dwordx4 v[2:3], off
	s_mov_b32 m0, s15
	v_lshl_add_u64 v[2:3], v[20:21], 0, s[26:27]
	s_add_i32 s14, s46, 0xa000
	s_mov_b32 s15, m0
	s_mov_b32 m0, s14
	s_nop 0
	global_load_lds_dwordx4 v[2:3], off
	s_mov_b32 m0, s15
	s_mov_b64 s[14:15], 0xc0800
	v_lshl_add_u64 v[2:3], v[22:23], 0, s[14:15]
	s_add_i32 s14, s46, 0xc000
	v_and_b32_e32 v25, 31, v24
	s_add_i32 s45, s45, s40
	s_mov_b32 s15, m0
	s_mov_b32 m0, s14
	s_nop 0
	global_load_lds_dwordx4 v[2:3], off
	s_mov_b32 m0, s15
	v_lshl_add_u64 v[2:3], v[18:19], 0, s[28:29]
	s_add_i32 s14, s46, 0xe000
	v_bfe_u32 v26, v24, 5, 1
	s_mov_b32 s15, m0
	s_mov_b32 m0, s14
	s_nop 0
	global_load_lds_dwordx4 v[2:3], off
	s_mov_b32 m0, s15
	v_lshl_add_u64 v[2:3], v[20:21], 0, s[28:29]
	s_add_i32 s14, s46, 0x10000
	v_or_b32_e32 v212, s45, v25
	s_mov_b32 s15, m0
	s_mov_b32 m0, s14
	s_nop 0
	global_load_lds_dwordx4 v[2:3], off
	s_mov_b32 m0, s15
	v_lshlrev_b32_e32 v0, 4, v26
	v_mad_i64_i32 v[2:3], s[14:15], v212, s59, v[4:5]
	v_lshl_add_u64 v[14:15], v[2:3], 0, v[0:1]
	global_load_dwordx4 v[2:5], v[14:15], off
	global_load_dwordx4 v[6:9], v[14:15], off offset:32
	global_load_dwordx4 v[10:13], v[14:15], off offset:64
	s_nop 0
	global_load_dwordx4 v[14:17], v[14:15], off offset:96
	s_mov_b64 s[14:15], 0x120800
	v_lshlrev_b32_e32 v213, 7, v25
	v_lshlrev_b32_e32 v214, 10, v26
	v_lshlrev_b32_e32 v223, 2, v26
	v_lshl_add_u64 v[166:167], v[20:21], 0, s[30:31]
	v_lshl_add_u64 v[168:169], v[18:19], 0, s[30:31]
	v_lshl_add_u64 v[170:171], v[22:23], 0, s[14:15]
	s_mov_b32 s53, 63
	s_mov_b32 s54, 3
	s_mov_b32 s55, 0
	s_or_b32 s56, s45, 31
	v_mov_b32_e32 v227, 0
	s_mov_b32 s57, s44
	s_mov_b64 s[14:15], 0
	s_mov_b32 s58, 3
	s_waitcnt vmcnt(3)
	s_nop 0
	v_lshlrev_b32_e32 v0, 16, v2
	v_and_b32_e32 v2, 0xffff0000, v2
	v_mul_f32_e32 v2, 0x3e38aa3b, v2
	s_waitcnt vmcnt(2)
	s_waitcnt vmcnt(1)
	s_waitcnt vmcnt(0)
; DI unsigned cvt_pk_bf16(float lo, float hi) { unsigned r; asm volatile("v_cvt_pk_bf16_f32 %0, %1, %2" : "=v"(r) : "v"(lo), "v"(hi)); return r; }
; DI float bf_lo(unsigned w) { return __uint_as_float(w << 16); }
; DI float bf_hi(unsigned w) { return __uint_as_float(w & 0xffff0000u); }
; template <int DK>
; DI void attn_pass(const AttnSrc& s, const int q0, const float sc, LAS unsigned char* lds, f32x16 (&O)[4]) {
;     ...
;   for (int i = 0; i < NS; ++i) qf[i] = *(const bf16x8*)(s.q + (size_t)(qw0 + r) * s.ldq + 16 * i + 8 * h);
; #pragma unroll
;   for (int i = 0; i < NS; ++i) asm volatile("" : "+v"(qf[i]));
;   constexpr bool REL = (DK == 64);
;   if (REL) {
; #pragma unroll
;   for (int i = 0; i < NS; ++i) {
;     const u32x4 w = __builtin_bit_cast(u32x4, qf[i]); u32x4 o;
;     o.x = cvt_pk_bf16(bf_lo(w.x) * sc, bf_hi(w.x) * sc); o.y = cvt_pk_bf16(bf_lo(w.y) * sc, bf_hi(w.y) * sc);
;     o.z = cvt_pk_bf16(bf_lo(w.z) * sc, bf_hi(w.z) * sc); o.w = cvt_pk_bf16(bf_lo(w.w) * sc, bf_hi(w.w) * sc);
;     qf[i] = __builtin_bit_cast(bf16x8, o);
;   }
;   }
;   f32x16 negm;
; #pragma unroll
;   for (int j = 0; j < 16; ++j) negm[j] = 0.f;
;   if (REL) asm volatile("" : "+v"(negm));
;   const int kx = (DK == 64) ? (r & 7) : ((r >> 1) & 7);
;   const int krow = r * ROWB;
;   const int i15 = lane & 15;
;   const int vrow = (4 * h + (i15 >> 2)) * 256 + ((lane >> 4) & 1) * 32 + (lane & 3) * 8;
;   const int vx = (i15 >> 2) & 3;
;   int buf = 0, pbuf = DPF;
	v_lshlrev_b32_e32 v29, 16, v5
	v_mul_f32_e32 v0, 0x3e38aa3b, v0
	v_cvt_pk_bf16_f32 v128, v0, v2
	v_and_b32_e32 v2, 0xffff0000, v5
	v_lshlrev_b32_e32 v27, 16, v3
	v_and_b32_e32 v3, 0xffff0000, v3
	v_lshlrev_b32_e32 v28, 16, v4
	v_and_b32_e32 v4, 0xffff0000, v4
	v_mul_f32_e32 v0, 0x3e38aa3b, v29
	v_mul_f32_e32 v2, 0x3e38aa3b, v2
	v_mul_f32_e32 v27, 0x3e38aa3b, v27
	v_mul_f32_e32 v3, 0x3e38aa3b, v3
	v_mul_f32_e32 v28, 0x3e38aa3b, v28
	v_mul_f32_e32 v4, 0x3e38aa3b, v4
	v_cvt_pk_bf16_f32 v129, v27, v3
	v_cvt_pk_bf16_f32 v130, v28, v4
	v_cvt_pk_bf16_f32 v131, v0, v2
	v_lshlrev_b32_e32 v0, 16, v6
	v_and_b32_e32 v2, 0xffff0000, v6
	v_mul_f32_e32 v0, 0x3e38aa3b, v0
	v_mul_f32_e32 v2, 0x3e38aa3b, v2
	v_cvt_pk_bf16_f32 v132, v0, v2
	v_lshlrev_b32_e32 v0, 16, v7
	v_and_b32_e32 v2, 0xffff0000, v7
	v_mul_f32_e32 v0, 0x3e38aa3b, v0
	v_mul_f32_e32 v2, 0x3e38aa3b, v2
	v_cvt_pk_bf16_f32 v133, v0, v2
	v_lshlrev_b32_e32 v0, 16, v8
	v_and_b32_e32 v2, 0xffff0000, v8
	v_mul_f32_e32 v0, 0x3e38aa3b, v0
	v_mul_f32_e32 v2, 0x3e38aa3b, v2
	v_cvt_pk_bf16_f32 v134, v0, v2
	v_lshlrev_b32_e32 v0, 16, v9
	v_and_b32_e32 v2, 0xffff0000, v9
	v_mul_f32_e32 v0, 0x3e38aa3b, v0
	v_mul_f32_e32 v2, 0x3e38aa3b, v2
	v_cvt_pk_bf16_f32 v135, v0, v2
	v_lshlrev_b32_e32 v0, 16, v10
	v_and_b32_e32 v2, 0xffff0000, v10
	v_mul_f32_e32 v0, 0x3e38aa3b, v0
	v_mul_f32_e32 v2, 0x3e38aa3b, v2
	v_cvt_pk_bf16_f32 v136, v0, v2
	v_lshlrev_b32_e32 v0, 16, v11
	v_and_b32_e32 v2, 0xffff0000, v11
	v_mul_f32_e32 v0, 0x3e38aa3b, v0
	v_mul_f32_e32 v2, 0x3e38aa3b, v2
	v_cvt_pk_bf16_f32 v137, v0, v2
	v_lshlrev_b32_e32 v0, 16, v12
	v_and_b32_e32 v2, 0xffff0000, v12
	v_mul_f32_e32 v0, 0x3e38aa3b, v0
	v_mul_f32_e32 v2, 0x3e38aa3b, v2
	v_cvt_pk_bf16_f32 v138, v0, v2
	v_lshlrev_b32_e32 v0, 16, v13
	v_and_b32_e32 v2, 0xffff0000, v13
	v_mul_f32_e32 v0, 0x3e38aa3b, v0
	v_mul_f32_e32 v2, 0x3e38aa3b, v2
	v_cvt_pk_bf16_f32 v139, v0, v2
	v_lshlrev_b32_e32 v0, 16, v14
	v_and_b32_e32 v2, 0xffff0000, v14
	v_mul_f32_e32 v0, 0x3e38aa3b, v0
	v_mul_f32_e32 v2, 0x3e38aa3b, v2
	v_cvt_pk_bf16_f32 v140, v0, v2
	v_lshlrev_b32_e32 v0, 16, v15
	v_and_b32_e32 v2, 0xffff0000, v15
	v_mul_f32_e32 v0, 0x3e38aa3b, v0
	v_mul_f32_e32 v2, 0x3e38aa3b, v2
	v_cvt_pk_bf16_f32 v141, v0, v2
	v_lshlrev_b32_e32 v0, 16, v16
	v_and_b32_e32 v2, 0xffff0000, v16
	v_mul_f32_e32 v0, 0x3e38aa3b, v0
	v_mul_f32_e32 v2, 0x3e38aa3b, v2
	v_cvt_pk_bf16_f32 v142, v0, v2
	v_lshlrev_b32_e32 v0, 16, v17
	v_and_b32_e32 v2, 0xffff0000, v17
	v_lshlrev_b32_e32 v17, 1, v24
	v_and_b32_e32 v216, 32, v17
	v_lshlrev_b32_e32 v17, 3, v24
	v_bfe_u32 v16, v24, 2, 2
	v_and_b32_e32 v217, 24, v17
	v_and_b32_e32 v17, 7, v24
	v_bitop3_b32 v24, v26, v24, 7 bitop3:0x78
	v_lshlrev_b32_e32 v218, 4, v24
	v_bitop3_b32 v24, v26, v17, 2 bitop3:0x36
	v_mul_f32_e32 v0, 0x3e38aa3b, v0
	v_mul_f32_e32 v2, 0x3e38aa3b, v2
	v_mov_b32_e32 v14, v1
	v_mov_b32_e32 v15, v1
	v_lshlrev_b32_e32 v219, 4, v24
	v_bitop3_b32 v24, v26, v17, 4 bitop3:0x36
	v_bitop3_b32 v17, v26, v17, 6 bitop3:0x36
	v_cvt_pk_bf16_f32 v143, v0, v2
	v_mov_b32_e32 v0, v1
	v_mov_b32_e32 v2, v1
	v_mov_b32_e32 v3, v1
	v_mov_b32_e32 v4, v1
	v_mov_b32_e32 v5, v1
	v_mov_b32_e32 v6, v1
	v_mov_b32_e32 v7, v1
	v_mov_b32_e32 v8, v1
	v_mov_b32_e32 v9, v1
	v_mov_b32_e32 v10, v1
	v_mov_b32_e32 v11, v1
	v_mov_b32_e32 v12, v1
	v_mov_b32_e32 v13, v1
	v_mov_b64_e32 v[94:95], v[14:15]
	v_lshlrev_b32_e32 v215, 8, v16
	v_lshlrev_b32_e32 v220, 4, v24
	v_lshlrev_b32_e32 v221, 4, v17
	v_lshlrev_b32_e32 v222, 6, v16
	v_mov_b64_e32 v[30:31], v[14:15]
	v_mov_b64_e32 v[46:47], v[14:15]
	v_mov_b64_e32 v[62:63], v[14:15]
	v_mov_b64_e32 v[78:79], v[14:15]
	v_mov_b64_e32 v[92:93], v[12:13]
	v_mov_b64_e32 v[90:91], v[10:11]
	v_mov_b64_e32 v[88:89], v[8:9]
	v_mov_b64_e32 v[86:87], v[6:7]
	v_mov_b64_e32 v[84:85], v[4:5]
	v_mov_b64_e32 v[82:83], v[2:3]
	v_mov_b64_e32 v[80:81], v[0:1]
	v_xor_b32_e32 v224, 64, v222
	v_xor_b32_e32 v225, 0x80, v222
	v_xor_b32_e32 v226, 0xc0, v222
	v_mov_b64_e32 v[28:29], v[12:13]
	v_mov_b64_e32 v[26:27], v[10:11]
	v_mov_b64_e32 v[24:25], v[8:9]
	v_mov_b64_e32 v[22:23], v[6:7]
	v_mov_b64_e32 v[20:21], v[4:5]
	v_mov_b64_e32 v[18:19], v[2:3]
	v_mov_b64_e32 v[16:17], v[0:1]
	v_mov_b64_e32 v[44:45], v[12:13]
	v_mov_b64_e32 v[42:43], v[10:11]
	v_mov_b64_e32 v[40:41], v[8:9]
	v_mov_b64_e32 v[38:39], v[6:7]
	v_mov_b64_e32 v[36:37], v[4:5]
	v_mov_b64_e32 v[34:35], v[2:3]
	v_mov_b64_e32 v[32:33], v[0:1]
	v_mov_b64_e32 v[60:61], v[12:13]
	v_mov_b64_e32 v[58:59], v[10:11]
	v_mov_b64_e32 v[56:57], v[8:9]
	v_mov_b64_e32 v[54:55], v[6:7]
	v_mov_b64_e32 v[52:53], v[4:5]
	v_mov_b64_e32 v[50:51], v[2:3]
	v_mov_b64_e32 v[48:49], v[0:1]
	v_mov_b64_e32 v[76:77], v[12:13]
	v_mov_b64_e32 v[74:75], v[10:11]
	v_mov_b64_e32 v[72:73], v[8:9]
	v_mov_b64_e32 v[70:71], v[6:7]
	v_mov_b64_e32 v[68:69], v[4:5]
	v_mov_b64_e32 v[66:67], v[2:3]
	v_mov_b64_e32 v[64:65], v[0:1]
	v_mov_b32_e32 v14, 0
	s_branch .LBB0_102

; template <int DK>
; DI void attn_pass(const AttnSrc& s, const int q0, const float sc, LAS unsigned char* lds, f32x16 (&O)[4]) {
;     ...
;     { const int rem = NT - 1 - t;
;       if (rem >= DPF - 1) asm volatile("s_waitcnt vmcnt(%0)" :: "n"((DPF - 1) * PT) : "memory");
;       else if (rem == 1) asm volatile("s_waitcnt vmcnt(%0)" :: "n"(PT) : "memory");
;       else asm volatile("s_waitcnt vmcnt(0)" ::: "memory"); }
;     __builtin_amdgcn_s_barrier();
.LBB0_102:
	s_cmp_lt_i32 s57, 2
	s_mov_b64 s[18:19], -1
	s_cbranch_scc0 .LBB0_108
	s_cmp_lg_u32 s43, s14
	s_cbranch_scc0 .LBB0_105
	s_waitcnt vmcnt(0)
	s_mov_b64 s[18:19], 0
.LBB0_105:
	s_andn2_b64 vcc, exec, s[18:19]
	s_cbranch_vccnz .LBB0_107
	s_waitcnt vmcnt(3)

; template <int DK>
; DI void attn_pass(const AttnSrc& s, const int q0, const float sc, LAS unsigned char* lds, f32x16 (&O)[4]) {
;     ...
;     { const int rem = NT - 1 - t;
;       if (rem >= DPF - 1) asm volatile("s_waitcnt vmcnt(%0)" :: "n"((DPF - 1) * PT) : "memory");
;       else if (rem == 1) asm volatile("s_waitcnt vmcnt(%0)" :: "n"(PT) : "memory");
;       else asm volatile("s_waitcnt vmcnt(0)" ::: "memory"); }
.LBB0_108:
	s_andn2_b64 vcc, exec, s[18:19]
	s_cbranch_vccnz .LBB0_110
	s_waitcnt vmcnt(6)

; DI float max3f(float a, float b, float c) { float r; asm("v_max3_f32 %0, %1, %2, %3" : "=v"(r) : "v"(a), "v"(b), "v"(c)); return r; }
; template <int DK>
; DI void attn_pass(const AttnSrc& s, const int q0, const float sc, LAS unsigned char* lds, f32x16 (&O)[4]) {
;     ...
;       float mx;
;       { float ma = max3f(p0[0], p0[1], p1[0]), mb = max3f(p0[2], p0[3], p1[1]); ma = max3f(ma, p1[2], p1[3]);
; #pragma unroll
;         for (int j = 4; j < 16; j += 4) { ma = max3f(ma, p0[j], p0[j + 1]); mb = max3f(mb, p0[j + 2], p0[j + 3]); ma = max3f(ma, p1[j], p1[j + 1]); mb = max3f(mb, p1[j + 2], p1[j + 3]); }
;         mx = fmaxf(ma, mb); }
;       { auto rr = __builtin_amdgcn_permlane32_swap(__float_as_uint(mx), __float_as_uint(mx), false, false); mx = fmaxf(__uint_as_float(rr[0]), __uint_as_float(rr[1])); }
;       float rs = 0.f;
;       if (REL) {
;         const bool grow = (mx > 8.f) || (t == 0);
;         if (__builtin_amdgcn_ballot_w64(grow) != 0ull) {
;           const float dl = grow ? mx : 0.f;
;           const float alpha = __builtin_amdgcn_exp2f(-dl);
;           mrun += dl; lrun *= alpha;
; #pragma unroll
;           for (int j = 0; j < 16; ++j) { p0[j] -= dl; p1[j] -= dl; negm[j] = -mrun; }
;           asm volatile("" : "+v"(negm));
; #pragma unroll
;           for (int i = 0; i < 4; ++i)
; #pragma unroll
;             for (int j = 0; j < 16; ++j) O[i][j] *= alpha;
;         }
.LBB0_115:
	s_nop 15
	s_nop 7
	s_mov_b32 s18, 0x41000000
	v_max3_f32 v0, v112, v113, v96
	v_max3_f32 v230, v114, v115, v97
	s_cmp_eq_u32 s53, 63
	v_max3_f32 v0, v0, v98, v99
	v_max3_f32 v230, v230, v118, v119
	s_nop 0
	v_max3_f32 v0, v0, v116, v117
	v_max3_f32 v230, v230, v102, v103
	s_nop 0
	v_max3_f32 v0, v0, v100, v101
	v_max3_f32 v230, v230, v122, v123
	s_nop 0
	v_max3_f32 v0, v0, v120, v121
	v_max3_f32 v230, v230, v106, v107
	s_nop 0
	v_max3_f32 v0, v0, v104, v105
	v_max3_f32 v230, v230, v126, v127
	s_nop 0
	v_max3_f32 v0, v0, v124, v125
	v_max3_f32 v230, v230, v110, v111
	s_nop 0
	v_max3_f32 v0, v0, v108, v109
	v_max_f32_e32 v230, v230, v230
	v_max_f32_e32 v0, v0, v0
	v_max_f32_e32 v0, v0, v230
	v_mov_b32_e32 v230, v0
	s_nop 1
	v_permlane32_swap_b32_e32 v0, v230
	v_max_f32_e32 v230, v230, v230
	v_max_f32_e32 v0, v0, v0
	v_max_f32_e32 v0, v0, v230
	v_cmp_lt_f32_e32 vcc, s18, v0
	s_cselect_b64 s[18:19], -1, 0
	s_or_b64 vcc, s[18:19], vcc
	s_cbranch_vccz .LBB0_100
	v_cndmask_b32_e32 v0, 0, v0, vcc
	v_add_f32_e32 v227, v227, v0
	v_pk_add_f32 v[112:113], v[112:113], v[0:1] op_sel_hi:[1,0] neg_lo:[0,1] neg_hi:[0,1]
	v_pk_add_f32 v[96:97], v[96:97], v[0:1] op_sel_hi:[1,0] neg_lo:[0,1] neg_hi:[0,1]
	v_pk_add_f32 v[114:115], v[114:115], v[0:1] op_sel_hi:[1,0] neg_lo:[0,1] neg_hi:[0,1]
	v_pk_add_f32 v[98:99], v[98:99], v[0:1] op_sel_hi:[1,0] neg_lo:[0,1] neg_hi:[0,1]
	v_pk_add_f32 v[116:117], v[116:117], v[0:1] op_sel_hi:[1,0] neg_lo:[0,1] neg_hi:[0,1]
	v_pk_add_f32 v[100:101], v[100:101], v[0:1] op_sel_hi:[1,0] neg_lo:[0,1] neg_hi:[0,1]
	v_pk_add_f32 v[118:119], v[118:119], v[0:1] op_sel_hi:[1,0] neg_lo:[0,1] neg_hi:[0,1]
	v_pk_add_f32 v[102:103], v[102:103], v[0:1] op_sel_hi:[1,0] neg_lo:[0,1] neg_hi:[0,1]
	v_pk_add_f32 v[120:121], v[120:121], v[0:1] op_sel_hi:[1,0] neg_lo:[0,1] neg_hi:[0,1]
	v_pk_add_f32 v[104:105], v[104:105], v[0:1] op_sel_hi:[1,0] neg_lo:[0,1] neg_hi:[0,1]
	v_pk_add_f32 v[122:123], v[122:123], v[0:1] op_sel_hi:[1,0] neg_lo:[0,1] neg_hi:[0,1]
	v_pk_add_f32 v[106:107], v[106:107], v[0:1] op_sel_hi:[1,0] neg_lo:[0,1] neg_hi:[0,1]
	v_pk_add_f32 v[124:125], v[124:125], v[0:1] op_sel_hi:[1,0] neg_lo:[0,1] neg_hi:[0,1]
	v_pk_add_f32 v[108:109], v[108:109], v[0:1] op_sel_hi:[1,0] neg_lo:[0,1] neg_hi:[0,1]
	v_pk_add_f32 v[126:127], v[126:127], v[0:1] op_sel_hi:[1,0] neg_lo:[0,1] neg_hi:[0,1]
	v_pk_add_f32 v[110:111], v[110:111], v[0:1] op_sel_hi:[1,0] neg_lo:[0,1] neg_hi:[0,1]
	v_exp_f32_e64 v0, -v0
	v_xor_b32_e32 v80, 0x80000000, v227
	v_mov_b32_e32 v81, v80
	v_mov_b32_e32 v82, v80
	v_mov_b32_e32 v83, v80
	v_mov_b32_e32 v84, v80
	v_mov_b32_e32 v85, v80
	v_mov_b32_e32 v86, v80
	v_mov_b32_e32 v87, v80
	v_mov_b32_e32 v88, v80
	v_mov_b32_e32 v89, v80
	v_mov_b32_e32 v90, v80
	v_mov_b32_e32 v91, v80
	v_mov_b32_e32 v92, v80
	v_mov_b32_e32 v93, v80
	v_mov_b32_e32 v94, v80
	v_mov_b32_e32 v95, v80
	v_pk_mul_f32 v[78:79], v[78:79], v[0:1] op_sel_hi:[1,0]
	v_pk_mul_f32 v[76:77], v[76:77], v[0:1] op_sel_hi:[1,0]
	v_pk_mul_f32 v[74:75], v[74:75], v[0:1] op_sel_hi:[1,0]
	v_pk_mul_f32 v[72:73], v[72:73], v[0:1] op_sel_hi:[1,0]
	v_pk_mul_f32 v[70:71], v[70:71], v[0:1] op_sel_hi:[1,0]
	v_pk_mul_f32 v[68:69], v[68:69], v[0:1] op_sel_hi:[1,0]
	v_pk_mul_f32 v[66:67], v[66:67], v[0:1] op_sel_hi:[1,0]
	v_pk_mul_f32 v[64:65], v[64:65], v[0:1] op_sel_hi:[1,0]
	v_pk_mul_f32 v[62:63], v[62:63], v[0:1] op_sel_hi:[1,0]
	v_pk_mul_f32 v[60:61], v[60:61], v[0:1] op_sel_hi:[1,0]
	v_pk_mul_f32 v[58:59], v[58:59], v[0:1] op_sel_hi:[1,0]
	v_pk_mul_f32 v[56:57], v[56:57], v[0:1] op_sel_hi:[1,0]
	v_pk_mul_f32 v[54:55], v[54:55], v[0:1] op_sel_hi:[1,0]
	v_pk_mul_f32 v[52:53], v[52:53], v[0:1] op_sel_hi:[1,0]
	v_pk_mul_f32 v[50:51], v[50:51], v[0:1] op_sel_hi:[1,0]
	v_pk_mul_f32 v[48:49], v[48:49], v[0:1] op_sel_hi:[1,0]
	v_pk_mul_f32 v[46:47], v[46:47], v[0:1] op_sel_hi:[1,0]
	v_pk_mul_f32 v[44:45], v[44:45], v[0:1] op_sel_hi:[1,0]
	v_pk_mul_f32 v[42:43], v[42:43], v[0:1] op_sel_hi:[1,0]
	v_pk_mul_f32 v[40:41], v[40:41], v[0:1] op_sel_hi:[1,0]
	v_pk_mul_f32 v[38:39], v[38:39], v[0:1] op_sel_hi:[1,0]
	v_pk_mul_f32 v[36:37], v[36:37], v[0:1] op_sel_hi:[1,0]
	v_pk_mul_f32 v[34:35], v[34:35], v[0:1] op_sel_hi:[1,0]
	v_pk_mul_f32 v[32:33], v[32:33], v[0:1] op_sel_hi:[1,0]
	v_pk_mul_f32 v[30:31], v[30:31], v[0:1] op_sel_hi:[1,0]
	v_pk_mul_f32 v[28:29], v[28:29], v[0:1] op_sel_hi:[1,0]
	v_pk_mul_f32 v[26:27], v[26:27], v[0:1] op_sel_hi:[1,0]
	v_pk_mul_f32 v[24:25], v[24:25], v[0:1] op_sel_hi:[1,0]
	v_pk_mul_f32 v[22:23], v[22:23], v[0:1] op_sel_hi:[1,0]
	v_pk_mul_f32 v[20:21], v[20:21], v[0:1] op_sel_hi:[1,0]
	v_pk_mul_f32 v[18:19], v[18:19], v[0:1] op_sel_hi:[1,0]
	v_pk_mul_f32 v[16:17], v[16:17], v[0:1] op_sel_hi:[1,0]
	v_mul_f32_e32 v14, v14, v0
	s_branch .LBB0_100
; DI unsigned cvt_pk_bf16(float lo, float hi) { unsigned r; asm volatile("v_cvt_pk_bf16_f32 %0, %1, %2" : "=v"(r) : "v"(lo), "v"(hi)); return r; }
; template <int DK>
; DI void attn_pass(const AttnSrc& s, const int q0, const float sc, LAS unsigned char* lds, f32x16 (&O)[4]) {
;     ...
;   asm volatile("s_waitcnt lgkmcnt(0)" ::: "memory");
;   __builtin_amdgcn_s_barrier();
;   asm volatile("" ::: "memory");
;   float lt; { auto rr = __builtin_amdgcn_permlane32_swap(__float_as_uint(lrun), __float_as_uint(lrun), false, false); lt = __uint_as_float(rr[0]) + __uint_as_float(rr[1]); }
;   const float inv = 1.f / lt;
; #pragma unroll
;   for (int i = 0; i < 4; ++i)
; #pragma unroll
;     for (int j = 0; j < 16; ++j) O[i][j] *= inv;
; }
; DI void phase_attention(KParams P, LAS unsigned char* lds) {
;     ...
;         if (map == 0) {
; #pragma unroll
;           for (int i = 0; i < 4; ++i)
; #pragma unroll
;             for (int j = 0; j < 8; ++j) o1p[i][j] = cvt_pk_bf16(O[i][2 * j], O[i][2 * j + 1]);
;         }
.LBB0_117:
	v_mov_b32_e32 v0, v14
	s_nop 1
	v_permlane32_swap_b32_e32 v14, v0
	v_add_f32_e32 v0, v14, v0
	v_div_scale_f32 v2, s[14:15], v0, v0, 1.0
	v_rcp_f32_e32 v3, v2
	s_waitcnt lgkmcnt(0)
	s_barrier
	v_fma_f32 v4, -v2, v3, 1.0
	v_fmac_f32_e32 v3, v4, v3
	v_div_scale_f32 v4, vcc, 1.0, v0, 1.0
	v_mul_f32_e32 v5, v4, v3
	v_fma_f32 v6, -v2, v5, v4
	v_fmac_f32_e32 v5, v6, v3
	v_fma_f32 v2, -v2, v5, v4
	v_div_fmas_f32 v2, v2, v3, v5
	v_div_fixup_f32 v92, v2, v0, 1.0
	v_mov_b32_e32 v2, v46
	v_mov_b32_e32 v3, v44
	v_mov_b32_e32 v44, v47
	v_mov_b32_e32 v6, v18
	v_mov_b32_e32 v7, v16
	v_mov_b32_e32 v16, v19
	v_mov_b32_e32 v10, v22
	v_mov_b32_e32 v11, v20
	v_mov_b32_e32 v20, v23
	v_mov_b32_e32 v14, v26
	v_mov_b32_e32 v15, v24
	v_mov_b32_e32 v24, v27
	v_mov_b32_e32 v18, v30
	v_mov_b32_e32 v19, v28
	v_mov_b32_e32 v28, v31
	v_mul_f32_e32 v0, v64, v92
	v_mul_f32_e32 v91, v65, v92
	v_mul_f32_e32 v90, v66, v92
	v_mul_f32_e32 v89, v67, v92
	v_mul_f32_e32 v88, v68, v92
	v_mul_f32_e32 v87, v69, v92
	v_mul_f32_e32 v86, v70, v92
	v_mul_f32_e32 v85, v71, v92
	v_mul_f32_e32 v84, v72, v92
	v_mul_f32_e32 v83, v73, v92
	v_mul_f32_e32 v82, v74, v92
	v_mul_f32_e32 v81, v75, v92
	v_mul_f32_e32 v80, v76, v92
	v_mul_f32_e32 v77, v77, v92
	v_mul_f32_e32 v76, v78, v92
	v_mul_f32_e32 v75, v79, v92
	v_mul_f32_e32 v74, v48, v92
	v_mul_f32_e32 v73, v49, v92
	v_mul_f32_e32 v72, v50, v92
	v_mul_f32_e32 v71, v51, v92
	v_mul_f32_e32 v70, v52, v92
	v_mul_f32_e32 v69, v53, v92
	v_mul_f32_e32 v68, v54, v92
	v_mul_f32_e32 v67, v55, v92
	v_mul_f32_e32 v66, v56, v92
	v_mul_f32_e32 v65, v57, v92
	v_mul_f32_e32 v64, v58, v92
	v_mul_f32_e32 v59, v59, v92
	v_mul_f32_e32 v58, v60, v92
	v_mul_f32_e32 v57, v61, v92
	v_mul_f32_e32 v56, v62, v92
	v_mul_f32_e32 v55, v63, v92
	v_mul_f32_e32 v54, v32, v92
	v_mul_f32_e32 v53, v33, v92
	v_mul_f32_e32 v52, v34, v92
	v_mul_f32_e32 v51, v35, v92
	v_mul_f32_e32 v50, v36, v92
	v_mul_f32_e32 v49, v37, v92
	v_mul_f32_e32 v48, v38, v92
	v_mul_f32_e32 v39, v39, v92
	v_mul_f32_e32 v38, v40, v92
	v_mul_f32_e32 v37, v41, v92
	v_mul_f32_e32 v5, v42, v92
	v_mul_f32_e32 v4, v43, v92
	v_pk_mul_f32 v[2:3], v[2:3], v[92:93] op_sel_hi:[1,0]
	v_pk_mul_f32 v[8:9], v[44:45], v[92:93] op_sel_hi:[1,0]
	v_pk_mul_f32 v[6:7], v[6:7], v[92:93] op_sel_hi:[1,0]
	v_pk_mul_f32 v[12:13], v[16:17], v[92:93] op_sel_hi:[1,0]
	v_pk_mul_f32 v[10:11], v[10:11], v[92:93] op_sel_hi:[1,0]
	v_pk_mul_f32 v[16:17], v[20:21], v[92:93] op_sel_hi:[1,0]
	v_pk_mul_f32 v[14:15], v[14:15], v[92:93] op_sel_hi:[1,0]
	v_pk_mul_f32 v[20:21], v[24:25], v[92:93] op_sel_hi:[1,0]
	v_pk_mul_f32 v[18:19], v[18:19], v[92:93] op_sel_hi:[1,0]
	s_andn2_b64 vcc, exec, s[12:13]
	v_pk_mul_f32 v[22:23], v[28:29], v[92:93] op_sel_hi:[1,0]
	s_cbranch_vccnz .LBB0_98
	v_cvt_pk_bf16_f32 v172, v0, v91
	v_cvt_pk_bf16_f32 v173, v90, v89
	v_cvt_pk_bf16_f32 v174, v88, v87
	v_cvt_pk_bf16_f32 v175, v86, v85
	v_cvt_pk_bf16_f32 v176, v84, v83
	v_cvt_pk_bf16_f32 v177, v82, v81
	v_cvt_pk_bf16_f32 v178, v80, v77
	v_cvt_pk_bf16_f32 v179, v76, v75
	v_cvt_pk_bf16_f32 v180, v74, v73
	v_cvt_pk_bf16_f32 v181, v72, v71
	v_cvt_pk_bf16_f32 v182, v70, v69
	v_cvt_pk_bf16_f32 v183, v68, v67
	v_cvt_pk_bf16_f32 v184, v66, v65
	v_cvt_pk_bf16_f32 v185, v64, v59
	v_cvt_pk_bf16_f32 v204, v58, v57
	v_cvt_pk_bf16_f32 v205, v56, v55
	v_cvt_pk_bf16_f32 v206, v54, v53
	v_cvt_pk_bf16_f32 v207, v52, v51
	v_cvt_pk_bf16_f32 v208, v50, v49
	v_cvt_pk_bf16_f32 v209, v48, v39
	v_cvt_pk_bf16_f32 v210, v38, v37
	v_cvt_pk_bf16_f32 v211, v5, v4
	v_cvt_pk_bf16_f32 v153, v3, v9
	v_cvt_pk_bf16_f32 v152, v2, v8
	v_cvt_pk_bf16_f32 v155, v7, v13
	v_cvt_pk_bf16_f32 v154, v6, v12
	v_cvt_pk_bf16_f32 v157, v11, v17
	v_cvt_pk_bf16_f32 v156, v10, v16
	v_cvt_pk_bf16_f32 v159, v15, v21
	v_cvt_pk_bf16_f32 v158, v14, v20
	v_cvt_pk_bf16_f32 v161, v19, v23
	v_cvt_pk_bf16_f32 v160, v18, v22
	s_branch .LBB0_98
.LBB0_119:
	s_add_u32 s17, s48, 0x9000000
	s_addc_u32 s18, s49, 0
	s_add_u32 s19, s48, 0xc000000
	s_addc_u32 s20, s49, 0
	v_readlane_b32 s21, v251, 0
	s_nop 1
	s_cmp_lg_u32 s3, 0x100
	s_cbranch_scc1 .Lxr_b
	s_and_b32 s4, s21, 7
	s_lshl_b32 s4, s4, 5
	s_lshr_b32 s5, s21, 3
	s_or_b32 s21, s4, s5
.Lxr_b:
	s_branch .LBB0_121
.LBB0_120:
	s_add_i32 s21, s21, s3
	s_cmpk_gt_i32 s21, 0xff
	s_cbranch_scc1 .LBB0_149
